# qk_prep rope half exchange via v_permlane32_swap instead of ds_bpermute
# baseline (speedup 1.0000x reference)
; __device__ __forceinline__ float bf2f(unsigned short h) { return __uint_as_float(((unsigned)h) << 16); }
; __device__ __forceinline__ unsigned short f2bf(float f) { return (unsigned short)(cvt_pk_bf16(f, 0.f) & 0xffffu); }
; __device__ __forceinline__ void pass_qk_prep(const Params& P) {
;     ...
;     for (int t = GWAVE_ID; t < T_TOK; t += GWAVES) {
;         float sn, cs; sincos_red((float)pos[t] * invf, sn, cs);
;         const float kpe = bf2f(ZB[(size_t)t * ZB_LD + 1024 + lane]);
; #pragma unroll
;         for (int h = 0; h < 8; ++h) {
;             bf16_t* q = QB + (size_t)t * 1536 + h * 192;
;             float a0 = bf2f(q[lane]), a1 = bf2f(q[64 + lane]), a2 = bf2f(q[128 + lane]);
;             float rs = rsqrtf(wave_sum(a0 * a0 + a1 * a1 + a2 * a2) * (1.f / 192.f) + EPS);
;             a0 *= rs * qn0; a1 *= rs * qn1; a2 *= rs * qn2;
;             float ot = __shfl_xor(a2, 32);
;             float r2 = lane < 32 ? a2 * cs - ot * sn : a2 * cs + ot * sn;
;             q[lane] = f2bf(a0 * QSC); q[64 + lane] = f2bf(a1 * QSC); q[128 + lane] = f2bf(r2 * QSC);
.LBB0_202:
	global_load_dword v1, v[2:3], off
	s_waitcnt lgkmcnt(0)
	v_lshl_add_u64 v[18:19], v[6:7], 0, v[180:181]
	s_mov_b32 s0, 0x19c00000
	v_lshl_add_u64 v[12:13], v[8:9], 0, v[180:181]
	v_add_u32_e32 v0, s74, v0
	v_lshl_add_u64 v[2:3], v[2:3], 0, s[96:97]
	v_lshl_add_u64 v[6:7], v[6:7], 0, s[6:7]
	v_lshl_add_u64 v[8:9], v[8:9], 0, s[10:11]
	s_waitcnt vmcnt(0)
	v_cvt_f32_i32_e32 v1, v1
	v_mul_f32_e32 v1, v36, v1
	v_mul_f32_e32 v10, 0.15915494, v1
	v_rndne_f32_e32 v10, v10
	v_fmac_f32_e32 v1, 0xc0c90000, v10
	v_fmac_f32_e32 v1, 0xbafdaa22, v10
	v_add_co_u32_e64 v10, s[0:1], s0, v18
	v_mul_f32_e32 v1, 0.15915494, v1
	s_nop 0
	v_addc_co_u32_e64 v11, s[0:1], 0, v19, s[0:1]
	v_lshl_add_u64 v[100:101], v[4:5], 0, v[180:181]
	v_add_co_u32_e64 v100, s[0:1], s14, v100
	s_nop 1
	v_addc_co_u32_e64 v101, s[0:1], 0, v101, s[0:1]
	global_load_ushort v56, v[10:11], off offset:128
	global_load_ushort v57, v[10:11], off
	global_load_ushort v58, v[10:11], off offset:256
	global_load_ushort v59, v[12:13], off
	global_load_ushort v60, v[100:101], off
	global_load_ushort v61, v[100:101], off offset:128
	global_load_ushort v62, v[10:11], off offset:512
	global_load_ushort v63, v[10:11], off offset:384
	global_load_ushort v64, v[10:11], off offset:640
	global_load_ushort v65, v[100:101], off offset:512
	global_load_ushort v66, v[100:101], off offset:640
	global_load_ushort v67, v[10:11], off offset:896
	global_load_ushort v68, v[10:11], off offset:768
	global_load_ushort v69, v[10:11], off offset:1024
	global_load_ushort v70, v[100:101], off offset:1024
	global_load_ushort v71, v[100:101], off offset:1152
	global_load_ushort v72, v[10:11], off offset:1280
	global_load_ushort v73, v[10:11], off offset:1152
	global_load_ushort v74, v[10:11], off offset:1408
	global_load_ushort v75, v[100:101], off offset:1536
	global_load_ushort v76, v[100:101], off offset:1664
	global_load_ushort v77, v[10:11], off offset:1664
	global_load_ushort v78, v[10:11], off offset:1536
	global_load_ushort v79, v[10:11], off offset:1792
	global_load_ushort v80, v[100:101], off offset:2048
	global_load_ushort v81, v[100:101], off offset:2176
	global_load_ushort v82, v[10:11], off offset:2048
	global_load_ushort v83, v[10:11], off offset:1920
	global_load_ushort v84, v[10:11], off offset:2176
	global_load_ushort v85, v[100:101], off offset:2560
	global_load_ushort v86, v[100:101], off offset:2688
	global_load_ushort v87, v[10:11], off offset:2432
	global_load_ushort v88, v[10:11], off offset:2304
	global_load_ushort v89, v[10:11], off offset:2560
	global_load_ushort v90, v[100:101], off offset:3072
	global_load_ushort v91, v[100:101], off offset:3200
	global_load_ushort v92, v[10:11], off offset:2816
	global_load_ushort v93, v[10:11], off offset:2688
	global_load_ushort v94, v[10:11], off offset:2944
	global_load_ushort v95, v[100:101], off offset:3584
	global_load_ushort v96, v[100:101], off offset:3712
	s_waitcnt vmcnt(0)
	v_lshl_add_u64 v[50:51], v[6:7], 0, v[48:49]
	global_load_dword v52, v[50:51], off
	v_lshl_add_u64 v[50:51], v[4:5], 0, v[54:55]
	global_load_dword v53, v[50:51], off
	v_mov_b32_e32 v14, v56
	v_sin_f32_e32 v43, v1
	v_cos_f32_e32 v1, v1
	v_lshlrev_b32_e32 v20, 16, v14
	v_mov_b32_e32 v14, v57
	v_mov_b32_e32 v15, v58
	v_mov_b32_e32 v24, v59
	v_lshlrev_b32_e32 v14, 16, v14
	v_lshlrev_b32_e32 v15, 16, v15
	v_pk_mul_f32 v[16:17], v[14:15], v[14:15]
	s_nop 0
	v_fma_f32 v16, v20, v20, v16
	v_add_f32_e32 v16, v16, v17
	s_nop 1
	v_mov_b32_dpp v17, v16 quad_perm:[1,0,3,2] row_mask:0xf bank_mask:0xf
	s_waitcnt lgkmcnt(0)
	v_add_f32_e32 v16, v16, v17
	s_nop 1
	v_mov_b32_dpp v17, v16 quad_perm:[2,3,0,1] row_mask:0xf bank_mask:0xf
	s_waitcnt lgkmcnt(0)
	v_add_f32_e32 v16, v16, v17
	s_nop 1
	v_mov_b32_dpp v17, v16 row_half_mirror row_mask:0xf bank_mask:0xf
	s_waitcnt lgkmcnt(0)
	v_add_f32_e32 v16, v16, v17
	s_nop 1
	v_mov_b32_dpp v17, v16 row_mirror row_mask:0xf bank_mask:0xf
	s_waitcnt lgkmcnt(0)
	v_add_f32_e32 v16, v16, v17
	v_mov_b32_e32 v17, v16
	s_nop 1
	v_permlane16_swap_b32 v16, v17
	s_waitcnt lgkmcnt(0)
	v_add_f32_e32 v16, v16, v17
	v_mov_b32_e32 v17, v16
	s_nop 1
	v_permlane32_swap_b32 v16, v17
	s_waitcnt lgkmcnt(0)
	v_add_f32_e32 v16, v16, v17
	v_fmamk_f32 v16, v16, 0x3baaaaab, v203
	v_cmp_gt_f32_e64 s[0:1], s71, v16
	v_mul_f32_e32 v17, 0x4b800000, v16
	s_nop 0
	v_cndmask_b32_e64 v16, v16, v17, s[0:1]
	v_rsq_f32_e32 v16, v16
	s_nop 0
	v_mul_f32_e32 v17, 0x45800000, v16
	v_cndmask_b32_e64 v16, v16, v17, s[0:1]
	v_mul_f32_e32 v17, v30, v16
	v_mul_f32_e32 v14, v17, v14
	v_mul_f32_e32 v17, v31, v16
	v_mul_f32_e32 v16, v34, v16
	v_mul_f32_e32 v15, v16, v15
	v_mov_b32_e32 v16, v15
	v_mov_b32_e32 v102, v15
	s_nop 1
	v_permlane32_swap_b32 v16, v102
	v_cndmask_b32_e32 v16, v16, v102, vcc
	v_mul_f32_e32 v17, v17, v20
	v_mul_f32_e32 v12, 0x3dd53b94, v17
	v_cvt_pk_bf16_f32 v12, v12, s0
	global_store_short v[10:11], v12, off offset:128
	s_waitcnt lgkmcnt(0)
	v_mul_f32_e32 v16, v43, v16
	v_cndmask_b32_e64 v16, v16, -v16, vcc
	v_fmac_f32_e32 v16, v1, v15
	v_mul_f32_e32 v12, 0x3dd53b94, v16
	v_cvt_pk_bf16_f32 v12, v12, s0
	v_mul_f32_e32 v14, 0x3dd53b94, v14
	global_store_short v[10:11], v12, off offset:256
	v_lshl_add_u64 v[12:13], v[4:5], 0, v[180:181]
	v_cvt_pk_bf16_f32 v14, v14, s0
	v_add_co_u32_e64 v12, s[0:1], s14, v12
	global_store_short v[10:11], v14, off
	s_nop 0
	v_addc_co_u32_e64 v13, s[0:1], 0, v13, s[0:1]
	v_mov_b32_e32 v14, v60
	v_mov_b32_e32 v15, v61
	v_lshl_add_u64 v[4:5], v[4:5], 0, s[2:3]
	v_lshlrev_b32_e32 v20, 16, v14
	v_mov_b32_e32 v14, v62
	v_lshlrev_b32_e32 v21, 16, v15
	v_pk_mul_f32 v[22:23], v[20:21], v[20:21]
	v_lshlrev_b32_e32 v25, 16, v14
	v_mov_b32_e32 v14, v63
	v_mov_b32_e32 v15, v64
	v_add_f32_e32 v22, v22, v23
	v_lshlrev_b32_e32 v14, 16, v14
	v_lshlrev_b32_e32 v15, 16, v15
	v_pk_mul_f32 v[16:17], v[14:15], v[14:15]
	s_nop 0
	v_fma_f32 v16, v25, v25, v16
	v_add_f32_e32 v16, v16, v17
	s_nop 1
	v_mov_b32_dpp v17, v16 quad_perm:[1,0,3,2] row_mask:0xf bank_mask:0xf
	s_waitcnt lgkmcnt(0)
; __device__ __forceinline__ float bf2f(unsigned short h) { return __uint_as_float(((unsigned)h) << 16); }
; __device__ __forceinline__ unsigned short f2bf(float f) { return (unsigned short)(cvt_pk_bf16(f, 0.f) & 0xffffu); }
; __device__ __forceinline__ void pass_qk_prep(const Params& P) {
;     ...
;         for (int h = 0; h < 8; ++h) {
;             bf16_t* q = QB + (size_t)t * 1536 + h * 192;
;             float a0 = bf2f(q[lane]), a1 = bf2f(q[64 + lane]), a2 = bf2f(q[128 + lane]);
;             float rs = rsqrtf(wave_sum(a0 * a0 + a1 * a1 + a2 * a2) * (1.f / 192.f) + EPS);
;             a0 *= rs * qn0; a1 *= rs * qn1; a2 *= rs * qn2;
;             float ot = __shfl_xor(a2, 32);
;             float r2 = lane < 32 ? a2 * cs - ot * sn : a2 * cs + ot * sn;
;             q[lane] = f2bf(a0 * QSC); q[64 + lane] = f2bf(a1 * QSC); q[128 + lane] = f2bf(r2 * QSC);
;             const bf16_t* kv = KVR + (size_t)t * 2048 + h * 256;
;             float b0 = bf2f(kv[lane]), b1 = bf2f(kv[64 + lane]), b2 = kpe;
;             rs = rsqrtf(wave_sum(b0 * b0 + b1 * b1 + b2 * b2) * (1.f / 192.f) + EPS);
;             b0 *= rs * kn0; b1 *= rs * kn1; b2 *= rs * kn2;
;             ot = __shfl_xor(b2, 32);
;             r2 = lane < 32 ? b2 * cs - ot * sn : b2 * cs + ot * sn;
;             bf16_t* k = KB + (size_t)t * 1536 + h * 192;
;             k[lane] = f2bf(b0); k[64 + lane] = f2bf(b1); k[128 + lane] = f2bf(r2);
	v_add_f32_e32 v16, v16, v17
	s_nop 1
	v_mov_b32_dpp v17, v16 quad_perm:[2,3,0,1] row_mask:0xf bank_mask:0xf
	s_waitcnt lgkmcnt(0)
	v_add_f32_e32 v16, v16, v17
	s_nop 1
	v_mov_b32_dpp v17, v16 row_half_mirror row_mask:0xf bank_mask:0xf
	s_waitcnt lgkmcnt(0)
	v_add_f32_e32 v16, v16, v17
	s_nop 1
	v_mov_b32_dpp v17, v16 row_mirror row_mask:0xf bank_mask:0xf
	s_waitcnt lgkmcnt(0)
	v_add_f32_e32 v16, v16, v17
	v_mov_b32_e32 v17, v16
	s_nop 1
	v_permlane16_swap_b32 v16, v17
	s_waitcnt lgkmcnt(0)
	v_add_f32_e32 v16, v16, v17
	v_mov_b32_e32 v17, v16
	s_nop 1
	v_permlane32_swap_b32 v16, v17
	s_waitcnt lgkmcnt(0)
	v_add_f32_e32 v16, v16, v17
	v_fmamk_f32 v16, v16, 0x3baaaaab, v203
	v_cmp_gt_f32_e64 s[0:1], s71, v16
	v_mul_f32_e32 v17, 0x4b800000, v16
	s_nop 0
	v_cndmask_b32_e64 v16, v16, v17, s[0:1]
	v_rsq_f32_e32 v16, v16
	s_nop 0
	v_mul_f32_e32 v17, 0x45800000, v16
	v_cndmask_b32_e64 v16, v16, v17, s[0:1]
	v_mul_f32_e32 v17, v30, v16
	v_mul_f32_e32 v14, v17, v14
	v_mul_f32_e32 v17, v31, v16
	v_mul_f32_e32 v16, v34, v16
	v_mul_f32_e32 v15, v16, v15
	v_mov_b32_e32 v16, v15
	v_mov_b32_e32 v102, v15
	s_nop 1
	v_permlane32_swap_b32 v16, v102
	v_cndmask_b32_e32 v16, v16, v102, vcc
	v_mul_f32_e32 v14, 0x3dd53b94, v14
	v_mul_f32_e32 v17, v17, v25
	v_cvt_pk_bf16_f32 v14, v14, s0
	global_store_short v[10:11], v14, off offset:384
	s_waitcnt lgkmcnt(0)
	v_mul_f32_e32 v16, v43, v16
	v_cndmask_b32_e64 v16, v16, -v16, vcc
	v_mul_f32_e32 v14, 0x3dd53b94, v17
	v_fmac_f32_e32 v16, v1, v15
	v_cvt_pk_bf16_f32 v14, v14, s0
	global_store_short v[10:11], v14, off offset:512
	v_mul_f32_e32 v14, 0x3dd53b94, v16
	v_cvt_pk_bf16_f32 v14, v14, s0
	global_store_short v[10:11], v14, off offset:640
	v_mov_b32_e32 v14, v65
	v_lshlrev_b32_e32 v15, 16, v14
	v_lshlrev_b32_e32 v14, 16, v24
	v_pk_mul_f32 v[16:17], v[14:15], v[14:15]
	s_nop 0
	v_add_f32_e32 v22, v16, v22
	s_nop 1
	v_mov_b32_dpp v23, v22 quad_perm:[1,0,3,2] row_mask:0xf bank_mask:0xf
	v_mov_b32_e32 v27, v17
	s_waitcnt lgkmcnt(0)
	v_add_f32_e32 v22, v22, v23
	s_nop 1
	v_mov_b32_dpp v23, v22 quad_perm:[2,3,0,1] row_mask:0xf bank_mask:0xf
	s_waitcnt lgkmcnt(0)
	v_add_f32_e32 v22, v22, v23
	s_nop 1
	v_mov_b32_dpp v23, v22 row_half_mirror row_mask:0xf bank_mask:0xf
	s_waitcnt lgkmcnt(0)
	v_add_f32_e32 v22, v22, v23
	s_nop 1
	v_mov_b32_dpp v23, v22 row_mirror row_mask:0xf bank_mask:0xf
	s_waitcnt lgkmcnt(0)
	v_add_f32_e32 v22, v22, v23
	v_mov_b32_e32 v23, v22
	s_nop 1
	v_permlane16_swap_b32 v22, v23
	s_waitcnt lgkmcnt(0)
	v_add_f32_e32 v22, v22, v23
	v_mov_b32_e32 v23, v22
	s_nop 1
	v_permlane32_swap_b32 v22, v23
	s_waitcnt lgkmcnt(0)
	v_add_f32_e32 v22, v22, v23
	v_fmamk_f32 v22, v22, 0x3baaaaab, v203
	v_cmp_gt_f32_e64 s[0:1], s71, v22
	v_mul_f32_e32 v23, 0x4b800000, v22
	s_nop 0
	v_cndmask_b32_e64 v22, v22, v23, s[0:1]
	v_rsq_f32_e32 v22, v22
	s_nop 0
	v_mul_f32_e32 v23, 0x45800000, v22
	v_cndmask_b32_e64 v22, v22, v23, s[0:1]
	v_mul_f32_e32 v23, v35, v22
	v_mul_f32_e32 v20, v23, v20
	v_mul_f32_e32 v23, v32, v22
	v_mul_f32_e32 v22, v33, v22
	v_mul_f32_e32 v22, v22, v14
	v_mul_f32_e32 v21, v23, v21
	v_mov_b32_e32 v23, v22
	v_mov_b32_e32 v102, v22
	s_nop 1
	v_permlane32_swap_b32 v23, v102
	v_cndmask_b32_e32 v23, v23, v102, vcc
	v_cvt_pk_bf16_f32 v20, v20, s0
	s_mov_b32 s0, 0x36000000
	v_add_co_u32_e64 v18, s[0:1], s0, v18
	s_waitcnt lgkmcnt(0)
	v_mul_f32_e32 v23, v43, v23
	v_cndmask_b32_e64 v23, v23, -v23, vcc
	v_addc_co_u32_e64 v19, s[0:1], 0, v19, s[0:1]
	v_fmac_f32_e32 v23, v1, v22
	v_mov_b32_e32 v22, v66
	s_nop 0
	global_store_short v[18:19], v20, off
	v_cvt_pk_bf16_f32 v20, v21, s0
	global_store_short v[18:19], v20, off offset:128
	v_cvt_pk_bf16_f32 v20, v23, s0
	global_store_short v[18:19], v20, off offset:256
	v_mov_b32_e32 v20, v67
	s_mov_b32 s0, 0x358637bd
	v_lshlrev_b32_e32 v23, 16, v22
	v_lshlrev_b32_e32 v22, 16, v20
	v_mov_b32_e32 v20, v68
	v_mov_b32_e32 v21, v69
	v_lshlrev_b32_e32 v24, 16, v20
	v_lshlrev_b32_e32 v25, 16, v21
	v_pk_mul_f32 v[20:21], v[24:25], v[24:25]
	s_nop 0
	v_mov_b32_e32 v26, v20
	v_pk_fma_f32 v[26:27], v[22:23], v[22:23], v[26:27]
	v_pk_mov_b32 v[20:21], v[20:21], v[16:17] op_sel:[1,0]
	s_nop 0
	v_pk_add_f32 v[20:21], v[26:27], v[20:21]
	s_nop 1
	v_mov_b32_dpp v27, v21 quad_perm:[1,0,3,2] row_mask:0xf bank_mask:0xf
	v_mov_b32_dpp v26, v20 quad_perm:[1,0,3,2] row_mask:0xf bank_mask:0xf
	s_waitcnt lgkmcnt(0)
	v_pk_add_f32 v[20:21], v[20:21], v[26:27]
	s_nop 1
	v_mov_b32_dpp v27, v21 quad_perm:[2,3,0,1] row_mask:0xf bank_mask:0xf
	v_mov_b32_dpp v26, v20 quad_perm:[2,3,0,1] row_mask:0xf bank_mask:0xf
	s_waitcnt lgkmcnt(0)
	v_pk_add_f32 v[20:21], v[20:21], v[26:27]
	s_nop 1
	v_mov_b32_dpp v27, v21 row_half_mirror row_mask:0xf bank_mask:0xf
	v_mov_b32_dpp v26, v20 row_half_mirror row_mask:0xf bank_mask:0xf
	s_waitcnt lgkmcnt(0)
	v_pk_add_f32 v[20:21], v[20:21], v[26:27]
	s_nop 1
	v_mov_b32_dpp v27, v21 row_mirror row_mask:0xf bank_mask:0xf
	v_mov_b32_dpp v26, v20 row_mirror row_mask:0xf bank_mask:0xf
	s_waitcnt lgkmcnt(0)
	v_pk_add_f32 v[20:21], v[20:21], v[26:27]
	v_mov_b32_e32 v27, v21
	v_mov_b32_e32 v26, v20
	s_nop 1
	v_permlane16_swap_b32 v21, v27
	v_permlane16_swap_b32 v20, v26
	s_waitcnt lgkmcnt(0)
	v_pk_add_f32 v[20:21], v[20:21], v[26:27]
	v_mov_b32_e32 v27, v21
	v_mov_b32_e32 v26, v20
	s_nop 1
	v_permlane32_swap_b32 v21, v27
	v_permlane32_swap_b32 v20, v26
	s_waitcnt lgkmcnt(0)
; __device__ __forceinline__ float bf2f(unsigned short h) { return __uint_as_float(((unsigned)h) << 16); }
; __device__ __forceinline__ unsigned short f2bf(float f) { return (unsigned short)(cvt_pk_bf16(f, 0.f) & 0xffffu); }
; __device__ __forceinline__ void pass_qk_prep(const Params& P) {
;     ...
;         for (int h = 0; h < 8; ++h) {
;             bf16_t* q = QB + (size_t)t * 1536 + h * 192;
;             float a0 = bf2f(q[lane]), a1 = bf2f(q[64 + lane]), a2 = bf2f(q[128 + lane]);
;             float rs = rsqrtf(wave_sum(a0 * a0 + a1 * a1 + a2 * a2) * (1.f / 192.f) + EPS);
;             a0 *= rs * qn0; a1 *= rs * qn1; a2 *= rs * qn2;
;             float ot = __shfl_xor(a2, 32);
;             float r2 = lane < 32 ? a2 * cs - ot * sn : a2 * cs + ot * sn;
;             q[lane] = f2bf(a0 * QSC); q[64 + lane] = f2bf(a1 * QSC); q[128 + lane] = f2bf(r2 * QSC);
;             const bf16_t* kv = KVR + (size_t)t * 2048 + h * 256;
;             float b0 = bf2f(kv[lane]), b1 = bf2f(kv[64 + lane]), b2 = kpe;
;             rs = rsqrtf(wave_sum(b0 * b0 + b1 * b1 + b2 * b2) * (1.f / 192.f) + EPS);
;             b0 *= rs * kn0; b1 *= rs * kn1; b2 *= rs * kn2;
;             ot = __shfl_xor(b2, 32);
;             r2 = lane < 32 ? b2 * cs - ot * sn : b2 * cs + ot * sn;
;             bf16_t* k = KB + (size_t)t * 1536 + h * 192;
;             k[lane] = f2bf(b0); k[64 + lane] = f2bf(b1); k[128 + lane] = f2bf(r2);
	v_pk_add_f32 v[26:27], v[20:21], v[26:27]
	v_mov_b64_e32 v[20:21], s[0:1]
	v_pk_fma_f32 v[26:27], v[26:27], s[16:17], v[20:21] op_sel_hi:[1,0,0]
	s_nop 0
	v_mul_f32_e32 v28, 0x4b800000, v27
	v_cmp_gt_f32_e64 s[38:39], s71, v27
	v_cmp_gt_f32_e64 s[0:1], s71, v26
	s_nop 0
	v_cndmask_b32_e64 v27, v27, v28, s[38:39]
	v_rsq_f32_e32 v27, v27
	s_nop 0
	v_mul_f32_e32 v28, 0x45800000, v27
	v_cndmask_b32_e64 v27, v27, v28, s[38:39]
	v_mul_f32_e32 v28, v35, v27
	v_mul_f32_e32 v15, v28, v15
	v_mul_f32_e32 v28, v32, v27
	v_mul_f32_e32 v27, v33, v27
	v_mul_f32_e32 v27, v27, v14
	v_mul_f32_e32 v23, v28, v23
	v_mov_b32_e32 v28, v27
	v_mov_b32_e32 v102, v27
	s_nop 1
	v_permlane32_swap_b32 v28, v102
	v_cndmask_b32_e32 v28, v28, v102, vcc
	v_cvt_pk_bf16_f32 v15, v15, s0
	global_store_short v[18:19], v15, off offset:384
	v_cvt_pk_bf16_f32 v15, v23, s0
	global_store_short v[18:19], v15, off offset:512
	s_waitcnt lgkmcnt(0)
	v_mul_f32_e32 v28, v43, v28
	v_cndmask_b32_e64 v28, v28, -v28, vcc
	v_fmac_f32_e32 v28, v1, v27
	v_cvt_pk_bf16_f32 v15, v28, s0
	global_store_short v[18:19], v15, off offset:640
	v_mul_f32_e32 v15, 0x4b800000, v26
	v_cndmask_b32_e64 v15, v26, v15, s[0:1]
	v_rsq_f32_e32 v15, v15
	s_nop 0
	v_mul_f32_e32 v23, 0x45800000, v15
	v_cndmask_b32_e64 v15, v15, v23, s[0:1]
	v_mul_f32_e32 v23, v30, v15
	v_mul_f32_e32 v23, v23, v24
	v_mul_f32_e32 v24, v31, v15
	v_mul_f32_e32 v15, v34, v15
	v_mul_f32_e32 v15, v15, v25
	v_mul_f32_e32 v22, v24, v22
	v_mov_b32_e32 v24, v15
	v_mov_b32_e32 v102, v15
	s_nop 1
	v_permlane32_swap_b32 v24, v102
	v_cndmask_b32_e32 v24, v24, v102, vcc
	s_waitcnt lgkmcnt(0)
	v_mul_f32_e32 v24, v43, v24
	v_cndmask_b32_e64 v24, v24, -v24, vcc
	v_fmac_f32_e32 v24, v1, v15
	v_mul_f32_e32 v15, 0x3dd53b94, v23
	v_cvt_pk_bf16_f32 v15, v15, s0
	global_store_short v[10:11], v15, off offset:768
	v_mul_f32_e32 v15, 0x3dd53b94, v22
	v_cvt_pk_bf16_f32 v15, v15, s0
	global_store_short v[10:11], v15, off offset:896
	v_mul_f32_e32 v15, 0x3dd53b94, v24
	v_cvt_pk_bf16_f32 v15, v15, s0
	global_store_short v[10:11], v15, off offset:1024
	v_mov_b32_e32 v15, v70
	s_nop 0
	v_mov_b32_e32 v22, v71
	v_lshlrev_b32_e32 v23, 16, v22
	v_lshlrev_b32_e32 v22, 16, v15
	v_mov_b32_e32 v15, v72
	v_mov_b32_e32 v27, v73
	v_mov_b32_e32 v28, v74
	v_pk_mul_f32 v[24:25], v[22:23], v[22:23]
	v_lshlrev_b32_e32 v15, 16, v15
	v_lshlrev_b32_e32 v29, 16, v28
	v_lshlrev_b32_e32 v28, 16, v27
	v_pk_mul_f32 v[44:45], v[28:29], v[28:29]
	v_mul_f32_e32 v26, v15, v15
	v_mov_b32_e32 v46, v44
	v_mov_b32_e32 v47, v24
	v_mov_b32_e32 v27, v25
	v_pk_add_f32 v[24:25], v[46:47], v[26:27]
	v_pk_mov_b32 v[26:27], v[44:45], v[16:17] op_sel:[1,0]
	s_nop 0
	v_pk_add_f32 v[24:25], v[24:25], v[26:27]
	s_nop 1
	v_mov_b32_dpp v27, v25 quad_perm:[1,0,3,2] row_mask:0xf bank_mask:0xf
	v_mov_b32_dpp v26, v24 quad_perm:[1,0,3,2] row_mask:0xf bank_mask:0xf
	s_waitcnt lgkmcnt(0)
	v_pk_add_f32 v[24:25], v[24:25], v[26:27]
	s_nop 1
	v_mov_b32_dpp v27, v25 quad_perm:[2,3,0,1] row_mask:0xf bank_mask:0xf
	v_mov_b32_dpp v26, v24 quad_perm:[2,3,0,1] row_mask:0xf bank_mask:0xf
	s_waitcnt lgkmcnt(0)
	v_pk_add_f32 v[24:25], v[24:25], v[26:27]
	s_nop 1
	v_mov_b32_dpp v27, v25 row_half_mirror row_mask:0xf bank_mask:0xf
	v_mov_b32_dpp v26, v24 row_half_mirror row_mask:0xf bank_mask:0xf
	s_waitcnt lgkmcnt(0)
	v_pk_add_f32 v[24:25], v[24:25], v[26:27]
	s_nop 1
	v_mov_b32_dpp v27, v25 row_mirror row_mask:0xf bank_mask:0xf
	v_mov_b32_dpp v26, v24 row_mirror row_mask:0xf bank_mask:0xf
	s_waitcnt lgkmcnt(0)
	v_pk_add_f32 v[24:25], v[24:25], v[26:27]
	v_mov_b32_e32 v27, v25
	v_mov_b32_e32 v26, v24
	s_nop 1
	v_permlane16_swap_b32 v25, v27
	v_permlane16_swap_b32 v24, v26
	s_waitcnt lgkmcnt(0)
	v_pk_add_f32 v[24:25], v[24:25], v[26:27]
	v_mov_b32_e32 v27, v25
	v_mov_b32_e32 v26, v24
	s_nop 1
	v_permlane32_swap_b32 v25, v27
	v_permlane32_swap_b32 v24, v26
	s_waitcnt lgkmcnt(0)
	v_pk_add_f32 v[24:25], v[24:25], v[26:27]
	s_nop 0
	v_pk_fma_f32 v[24:25], v[24:25], s[16:17], v[20:21] op_sel_hi:[1,0,0]
	s_nop 0
	v_mul_f32_e32 v26, 0x4b800000, v25
	v_cmp_gt_f32_e64 s[38:39], s71, v25
	v_cmp_gt_f32_e64 s[0:1], s71, v24
	s_nop 0
	v_cndmask_b32_e64 v25, v25, v26, s[38:39]
	v_rsq_f32_e32 v25, v25
	s_nop 0
	v_mul_f32_e32 v26, 0x45800000, v25
	v_cndmask_b32_e64 v25, v25, v26, s[38:39]
	v_mul_f32_e32 v26, v35, v25
	v_mul_f32_e32 v22, v26, v22
	v_mul_f32_e32 v26, v32, v25
	v_mul_f32_e32 v25, v33, v25
	v_mul_f32_e32 v25, v25, v14
	v_mul_f32_e32 v23, v26, v23
	v_mov_b32_e32 v26, v25
	v_mov_b32_e32 v102, v25
	s_nop 1
	v_permlane32_swap_b32 v26, v102
	v_cndmask_b32_e32 v26, v26, v102, vcc
	v_cvt_pk_bf16_f32 v22, v22, s0
	global_store_short v[18:19], v22, off offset:768
	v_cvt_pk_bf16_f32 v22, v23, s0
	global_store_short v[18:19], v22, off offset:896
	s_waitcnt lgkmcnt(0)
	v_mul_f32_e32 v26, v43, v26
	v_cndmask_b32_e64 v26, v26, -v26, vcc
	v_fmac_f32_e32 v26, v1, v25
	v_cvt_pk_bf16_f32 v22, v26, s0
	global_store_short v[18:19], v22, off offset:1024
	v_mul_f32_e32 v22, 0x4b800000, v24
	v_cndmask_b32_e64 v22, v24, v22, s[0:1]
	v_rsq_f32_e32 v22, v22
	s_nop 0
	v_mul_f32_e32 v23, 0x45800000, v22
	v_cndmask_b32_e64 v22, v22, v23, s[0:1]
	v_mul_f32_e32 v23, v30, v22
	v_mul_f32_e32 v24, v31, v22
	v_mul_f32_e32 v22, v34, v22
	v_mul_f32_e32 v22, v22, v29
	v_mul_f32_e32 v15, v24, v15
	v_mov_b32_e32 v24, v22
	v_mov_b32_e32 v102, v22
	s_nop 1
	v_permlane32_swap_b32 v24, v102
	v_cndmask_b32_e32 v24, v24, v102, vcc
	v_mul_f32_e32 v15, 0x3dd53b94, v15
	v_mul_f32_e32 v23, v23, v28
	v_cvt_pk_bf16_f32 v15, v15, s0
	global_store_short v[10:11], v15, off offset:1280
	s_waitcnt lgkmcnt(0)
; __device__ __forceinline__ float bf2f(unsigned short h) { return __uint_as_float(((unsigned)h) << 16); }
; __device__ __forceinline__ unsigned short f2bf(float f) { return (unsigned short)(cvt_pk_bf16(f, 0.f) & 0xffffu); }
; __device__ __forceinline__ void pass_qk_prep(const Params& P) {
;     ...
;         for (int h = 0; h < 8; ++h) {
;             bf16_t* q = QB + (size_t)t * 1536 + h * 192;
;             float a0 = bf2f(q[lane]), a1 = bf2f(q[64 + lane]), a2 = bf2f(q[128 + lane]);
;             float rs = rsqrtf(wave_sum(a0 * a0 + a1 * a1 + a2 * a2) * (1.f / 192.f) + EPS);
;             a0 *= rs * qn0; a1 *= rs * qn1; a2 *= rs * qn2;
;             float ot = __shfl_xor(a2, 32);
;             float r2 = lane < 32 ? a2 * cs - ot * sn : a2 * cs + ot * sn;
;             q[lane] = f2bf(a0 * QSC); q[64 + lane] = f2bf(a1 * QSC); q[128 + lane] = f2bf(r2 * QSC);
;             const bf16_t* kv = KVR + (size_t)t * 2048 + h * 256;
;             float b0 = bf2f(kv[lane]), b1 = bf2f(kv[64 + lane]), b2 = kpe;
;             rs = rsqrtf(wave_sum(b0 * b0 + b1 * b1 + b2 * b2) * (1.f / 192.f) + EPS);
;             b0 *= rs * kn0; b1 *= rs * kn1; b2 *= rs * kn2;
;             ot = __shfl_xor(b2, 32);
;             r2 = lane < 32 ? b2 * cs - ot * sn : b2 * cs + ot * sn;
;             bf16_t* k = KB + (size_t)t * 1536 + h * 192;
;             k[lane] = f2bf(b0); k[64 + lane] = f2bf(b1); k[128 + lane] = f2bf(r2);
	v_mul_f32_e32 v24, v43, v24
	v_cndmask_b32_e64 v24, v24, -v24, vcc
	v_fmac_f32_e32 v24, v1, v22
	v_mul_f32_e32 v22, 0x3dd53b94, v23
	v_mul_f32_e32 v15, 0x3dd53b94, v24
	v_cvt_pk_bf16_f32 v22, v22, s0
	v_cvt_pk_bf16_f32 v15, v15, s0
	global_store_short v[10:11], v22, off offset:1152
	global_store_short v[10:11], v15, off offset:1408
	v_mov_b32_e32 v15, v75
	s_nop 0
	v_mov_b32_e32 v22, v76
	v_lshlrev_b32_e32 v23, 16, v22
	v_lshlrev_b32_e32 v22, 16, v15
	v_mov_b32_e32 v15, v77
	v_mov_b32_e32 v27, v78
	v_mov_b32_e32 v28, v79
	v_pk_mul_f32 v[24:25], v[22:23], v[22:23]
	v_lshlrev_b32_e32 v15, 16, v15
	v_lshlrev_b32_e32 v29, 16, v28
	v_lshlrev_b32_e32 v28, 16, v27
	v_pk_mul_f32 v[44:45], v[28:29], v[28:29]
	v_mul_f32_e32 v26, v15, v15
	v_mov_b32_e32 v46, v44
	v_mov_b32_e32 v47, v24
	v_mov_b32_e32 v27, v25
	v_pk_add_f32 v[24:25], v[46:47], v[26:27]
	v_pk_mov_b32 v[26:27], v[44:45], v[16:17] op_sel:[1,0]
	s_nop 0
	v_pk_add_f32 v[24:25], v[24:25], v[26:27]
	s_nop 1
	v_mov_b32_dpp v27, v25 quad_perm:[1,0,3,2] row_mask:0xf bank_mask:0xf
	v_mov_b32_dpp v26, v24 quad_perm:[1,0,3,2] row_mask:0xf bank_mask:0xf
	s_waitcnt lgkmcnt(0)
	v_pk_add_f32 v[24:25], v[24:25], v[26:27]
	s_nop 1
	v_mov_b32_dpp v27, v25 quad_perm:[2,3,0,1] row_mask:0xf bank_mask:0xf
	v_mov_b32_dpp v26, v24 quad_perm:[2,3,0,1] row_mask:0xf bank_mask:0xf
	s_waitcnt lgkmcnt(0)
	v_pk_add_f32 v[24:25], v[24:25], v[26:27]
	s_nop 1
	v_mov_b32_dpp v27, v25 row_half_mirror row_mask:0xf bank_mask:0xf
	v_mov_b32_dpp v26, v24 row_half_mirror row_mask:0xf bank_mask:0xf
	s_waitcnt lgkmcnt(0)
	v_pk_add_f32 v[24:25], v[24:25], v[26:27]
	s_nop 1
	v_mov_b32_dpp v27, v25 row_mirror row_mask:0xf bank_mask:0xf
	v_mov_b32_dpp v26, v24 row_mirror row_mask:0xf bank_mask:0xf
	s_waitcnt lgkmcnt(0)
	v_pk_add_f32 v[24:25], v[24:25], v[26:27]
	v_mov_b32_e32 v27, v25
	v_mov_b32_e32 v26, v24
	s_nop 1
	v_permlane16_swap_b32 v25, v27
	v_permlane16_swap_b32 v24, v26
	s_waitcnt lgkmcnt(0)
	v_pk_add_f32 v[24:25], v[24:25], v[26:27]
	v_mov_b32_e32 v27, v25
	v_mov_b32_e32 v26, v24
	s_nop 1
	v_permlane32_swap_b32 v25, v27
	v_permlane32_swap_b32 v24, v26
	s_waitcnt lgkmcnt(0)
	v_pk_add_f32 v[24:25], v[24:25], v[26:27]
	s_nop 0
	v_pk_fma_f32 v[24:25], v[24:25], s[16:17], v[20:21] op_sel_hi:[1,0,0]
	s_nop 0
	v_mul_f32_e32 v26, 0x4b800000, v25
	v_cmp_gt_f32_e64 s[38:39], s71, v25
	v_cmp_gt_f32_e64 s[0:1], s71, v24
	s_nop 0
	v_cndmask_b32_e64 v25, v25, v26, s[38:39]
	v_rsq_f32_e32 v25, v25
	s_nop 0
	v_mul_f32_e32 v26, 0x45800000, v25
	v_cndmask_b32_e64 v25, v25, v26, s[38:39]
	v_mul_f32_e32 v26, v35, v25
	v_mul_f32_e32 v22, v26, v22
	v_mul_f32_e32 v26, v32, v25
	v_mul_f32_e32 v25, v33, v25
	v_mul_f32_e32 v25, v25, v14
	v_mul_f32_e32 v23, v26, v23
	v_mov_b32_e32 v26, v25
	v_mov_b32_e32 v102, v25
	s_nop 1
	v_permlane32_swap_b32 v26, v102
	v_cndmask_b32_e32 v26, v26, v102, vcc
	v_cvt_pk_bf16_f32 v22, v22, s0
	global_store_short v[18:19], v22, off offset:1152
	v_cvt_pk_bf16_f32 v22, v23, s0
	global_store_short v[18:19], v22, off offset:1280
	s_waitcnt lgkmcnt(0)
	v_mul_f32_e32 v26, v43, v26
	v_cndmask_b32_e64 v26, v26, -v26, vcc
	v_fmac_f32_e32 v26, v1, v25
	v_cvt_pk_bf16_f32 v22, v26, s0
	global_store_short v[18:19], v22, off offset:1408
	v_mul_f32_e32 v22, 0x4b800000, v24
	v_cndmask_b32_e64 v22, v24, v22, s[0:1]
	v_rsq_f32_e32 v22, v22
	s_nop 0
	v_mul_f32_e32 v23, 0x45800000, v22
	v_cndmask_b32_e64 v22, v22, v23, s[0:1]
	v_mul_f32_e32 v23, v30, v22
	v_mul_f32_e32 v24, v31, v22
	v_mul_f32_e32 v22, v34, v22
	v_mul_f32_e32 v22, v22, v29
	v_mul_f32_e32 v15, v24, v15
	v_mov_b32_e32 v24, v22
	v_mov_b32_e32 v102, v22
	s_nop 1
	v_permlane32_swap_b32 v24, v102
	v_cndmask_b32_e32 v24, v24, v102, vcc
	v_mul_f32_e32 v15, 0x3dd53b94, v15
	v_mul_f32_e32 v23, v23, v28
	v_cvt_pk_bf16_f32 v15, v15, s0
	global_store_short v[10:11], v15, off offset:1664
	s_waitcnt lgkmcnt(0)
	v_mul_f32_e32 v24, v43, v24
	v_cndmask_b32_e64 v24, v24, -v24, vcc
	v_fmac_f32_e32 v24, v1, v22
	v_mul_f32_e32 v22, 0x3dd53b94, v23
	v_mul_f32_e32 v15, 0x3dd53b94, v24
	v_cvt_pk_bf16_f32 v22, v22, s0
	v_cvt_pk_bf16_f32 v15, v15, s0
	global_store_short v[10:11], v22, off offset:1536
	global_store_short v[10:11], v15, off offset:1792
	v_mov_b32_e32 v15, v80
	s_nop 0
	v_mov_b32_e32 v22, v81
	v_lshlrev_b32_e32 v23, 16, v22
	v_lshlrev_b32_e32 v22, 16, v15
	v_mov_b32_e32 v15, v82
	v_mov_b32_e32 v27, v83
	v_mov_b32_e32 v28, v84
	v_pk_mul_f32 v[24:25], v[22:23], v[22:23]
	v_lshlrev_b32_e32 v15, 16, v15
	v_lshlrev_b32_e32 v29, 16, v28
	v_lshlrev_b32_e32 v28, 16, v27
	v_pk_mul_f32 v[44:45], v[28:29], v[28:29]
	v_mul_f32_e32 v26, v15, v15
	v_mov_b32_e32 v46, v44
	v_mov_b32_e32 v47, v24
	v_mov_b32_e32 v27, v25
	v_pk_add_f32 v[24:25], v[46:47], v[26:27]
	v_pk_mov_b32 v[26:27], v[44:45], v[16:17] op_sel:[1,0]
	s_nop 0
	v_pk_add_f32 v[24:25], v[24:25], v[26:27]
	s_nop 1
	v_mov_b32_dpp v27, v25 quad_perm:[1,0,3,2] row_mask:0xf bank_mask:0xf
	v_mov_b32_dpp v26, v24 quad_perm:[1,0,3,2] row_mask:0xf bank_mask:0xf
	s_waitcnt lgkmcnt(0)
	v_pk_add_f32 v[24:25], v[24:25], v[26:27]
	s_nop 1
	v_mov_b32_dpp v27, v25 quad_perm:[2,3,0,1] row_mask:0xf bank_mask:0xf
	v_mov_b32_dpp v26, v24 quad_perm:[2,3,0,1] row_mask:0xf bank_mask:0xf
	s_waitcnt lgkmcnt(0)
	v_pk_add_f32 v[24:25], v[24:25], v[26:27]
	s_nop 1
	v_mov_b32_dpp v27, v25 row_half_mirror row_mask:0xf bank_mask:0xf
	v_mov_b32_dpp v26, v24 row_half_mirror row_mask:0xf bank_mask:0xf
	s_waitcnt lgkmcnt(0)
	v_pk_add_f32 v[24:25], v[24:25], v[26:27]
	s_nop 1
	v_mov_b32_dpp v27, v25 row_mirror row_mask:0xf bank_mask:0xf
	v_mov_b32_dpp v26, v24 row_mirror row_mask:0xf bank_mask:0xf
	s_waitcnt lgkmcnt(0)
; __device__ __forceinline__ float bf2f(unsigned short h) { return __uint_as_float(((unsigned)h) << 16); }
; __device__ __forceinline__ unsigned short f2bf(float f) { return (unsigned short)(cvt_pk_bf16(f, 0.f) & 0xffffu); }
; __device__ __forceinline__ void pass_qk_prep(const Params& P) {
;     ...
;         for (int h = 0; h < 8; ++h) {
;             bf16_t* q = QB + (size_t)t * 1536 + h * 192;
;             float a0 = bf2f(q[lane]), a1 = bf2f(q[64 + lane]), a2 = bf2f(q[128 + lane]);
;             float rs = rsqrtf(wave_sum(a0 * a0 + a1 * a1 + a2 * a2) * (1.f / 192.f) + EPS);
;             a0 *= rs * qn0; a1 *= rs * qn1; a2 *= rs * qn2;
;             float ot = __shfl_xor(a2, 32);
;             float r2 = lane < 32 ? a2 * cs - ot * sn : a2 * cs + ot * sn;
;             q[lane] = f2bf(a0 * QSC); q[64 + lane] = f2bf(a1 * QSC); q[128 + lane] = f2bf(r2 * QSC);
;             const bf16_t* kv = KVR + (size_t)t * 2048 + h * 256;
;             float b0 = bf2f(kv[lane]), b1 = bf2f(kv[64 + lane]), b2 = kpe;
;             rs = rsqrtf(wave_sum(b0 * b0 + b1 * b1 + b2 * b2) * (1.f / 192.f) + EPS);
;             b0 *= rs * kn0; b1 *= rs * kn1; b2 *= rs * kn2;
;             ot = __shfl_xor(b2, 32);
;             r2 = lane < 32 ? b2 * cs - ot * sn : b2 * cs + ot * sn;
;             bf16_t* k = KB + (size_t)t * 1536 + h * 192;
;             k[lane] = f2bf(b0); k[64 + lane] = f2bf(b1); k[128 + lane] = f2bf(r2);
	v_pk_add_f32 v[24:25], v[24:25], v[26:27]
	v_mov_b32_e32 v27, v25
	v_mov_b32_e32 v26, v24
	s_nop 1
	v_permlane16_swap_b32 v25, v27
	v_permlane16_swap_b32 v24, v26
	s_waitcnt lgkmcnt(0)
	v_pk_add_f32 v[24:25], v[24:25], v[26:27]
	v_mov_b32_e32 v27, v25
	v_mov_b32_e32 v26, v24
	s_nop 1
	v_permlane32_swap_b32 v25, v27
	v_permlane32_swap_b32 v24, v26
	s_waitcnt lgkmcnt(0)
	v_pk_add_f32 v[24:25], v[24:25], v[26:27]
	s_nop 0
	v_pk_fma_f32 v[24:25], v[24:25], s[16:17], v[20:21] op_sel_hi:[1,0,0]
	s_nop 0
	v_mul_f32_e32 v26, 0x4b800000, v25
	v_cmp_gt_f32_e64 s[38:39], s71, v25
	v_cmp_gt_f32_e64 s[0:1], s71, v24
	s_nop 0
	v_cndmask_b32_e64 v25, v25, v26, s[38:39]
	v_rsq_f32_e32 v25, v25
	s_nop 0
	v_mul_f32_e32 v26, 0x45800000, v25
	v_cndmask_b32_e64 v25, v25, v26, s[38:39]
	v_mul_f32_e32 v26, v35, v25
	v_mul_f32_e32 v22, v26, v22
	v_mul_f32_e32 v26, v32, v25
	v_mul_f32_e32 v25, v33, v25
	v_mul_f32_e32 v25, v25, v14
	v_mul_f32_e32 v23, v26, v23
	v_mov_b32_e32 v26, v25
	v_mov_b32_e32 v102, v25
	s_nop 1
	v_permlane32_swap_b32 v26, v102
	v_cndmask_b32_e32 v26, v26, v102, vcc
	v_cvt_pk_bf16_f32 v22, v22, s0
	global_store_short v[18:19], v22, off offset:1536
	v_cvt_pk_bf16_f32 v22, v23, s0
	global_store_short v[18:19], v22, off offset:1664
	s_waitcnt lgkmcnt(0)
	v_mul_f32_e32 v26, v43, v26
	v_cndmask_b32_e64 v26, v26, -v26, vcc
	v_fmac_f32_e32 v26, v1, v25
	v_cvt_pk_bf16_f32 v22, v26, s0
	global_store_short v[18:19], v22, off offset:1792
	v_mul_f32_e32 v22, 0x4b800000, v24
	v_cndmask_b32_e64 v22, v24, v22, s[0:1]
	v_rsq_f32_e32 v22, v22
	s_nop 0
	v_mul_f32_e32 v23, 0x45800000, v22
	v_cndmask_b32_e64 v22, v22, v23, s[0:1]
	v_mul_f32_e32 v23, v30, v22
	v_mul_f32_e32 v24, v31, v22
	v_mul_f32_e32 v22, v34, v22
	v_mul_f32_e32 v22, v22, v29
	v_mul_f32_e32 v15, v24, v15
	v_mov_b32_e32 v24, v22
	v_mov_b32_e32 v102, v22
	s_nop 1
	v_permlane32_swap_b32 v24, v102
	v_cndmask_b32_e32 v24, v24, v102, vcc
	v_mul_f32_e32 v15, 0x3dd53b94, v15
	v_mul_f32_e32 v23, v23, v28
	v_cvt_pk_bf16_f32 v15, v15, s0
	global_store_short v[10:11], v15, off offset:2048
	s_waitcnt lgkmcnt(0)
	v_mul_f32_e32 v24, v43, v24
	v_cndmask_b32_e64 v24, v24, -v24, vcc
	v_fmac_f32_e32 v24, v1, v22
	v_mul_f32_e32 v22, 0x3dd53b94, v23
	v_mul_f32_e32 v15, 0x3dd53b94, v24
	v_cvt_pk_bf16_f32 v22, v22, s0
	v_cvt_pk_bf16_f32 v15, v15, s0
	global_store_short v[10:11], v22, off offset:1920
	global_store_short v[10:11], v15, off offset:2176
	v_mov_b32_e32 v15, v85
	s_nop 0
	v_mov_b32_e32 v22, v86
	v_lshlrev_b32_e32 v23, 16, v22
	v_lshlrev_b32_e32 v22, 16, v15
	v_mov_b32_e32 v15, v87
	v_mov_b32_e32 v27, v88
	v_mov_b32_e32 v28, v89
	v_pk_mul_f32 v[24:25], v[22:23], v[22:23]
	v_lshlrev_b32_e32 v15, 16, v15
	v_lshlrev_b32_e32 v29, 16, v28
	v_lshlrev_b32_e32 v28, 16, v27
	v_pk_mul_f32 v[44:45], v[28:29], v[28:29]
	v_mul_f32_e32 v26, v15, v15
	v_mov_b32_e32 v46, v44
	v_mov_b32_e32 v47, v24
	v_mov_b32_e32 v27, v25
	v_pk_add_f32 v[24:25], v[46:47], v[26:27]
	v_pk_mov_b32 v[26:27], v[44:45], v[16:17] op_sel:[1,0]
	s_nop 0
	v_pk_add_f32 v[24:25], v[24:25], v[26:27]
	s_nop 1
	v_mov_b32_dpp v27, v25 quad_perm:[1,0,3,2] row_mask:0xf bank_mask:0xf
	v_mov_b32_dpp v26, v24 quad_perm:[1,0,3,2] row_mask:0xf bank_mask:0xf
	s_waitcnt lgkmcnt(0)
	v_pk_add_f32 v[24:25], v[24:25], v[26:27]
	s_nop 1
	v_mov_b32_dpp v27, v25 quad_perm:[2,3,0,1] row_mask:0xf bank_mask:0xf
	v_mov_b32_dpp v26, v24 quad_perm:[2,3,0,1] row_mask:0xf bank_mask:0xf
	s_waitcnt lgkmcnt(0)
	v_pk_add_f32 v[24:25], v[24:25], v[26:27]
	s_nop 1
	v_mov_b32_dpp v27, v25 row_half_mirror row_mask:0xf bank_mask:0xf
	v_mov_b32_dpp v26, v24 row_half_mirror row_mask:0xf bank_mask:0xf
	s_waitcnt lgkmcnt(0)
	v_pk_add_f32 v[24:25], v[24:25], v[26:27]
	s_nop 1
	v_mov_b32_dpp v27, v25 row_mirror row_mask:0xf bank_mask:0xf
	v_mov_b32_dpp v26, v24 row_mirror row_mask:0xf bank_mask:0xf
	s_waitcnt lgkmcnt(0)
	v_pk_add_f32 v[24:25], v[24:25], v[26:27]
	v_mov_b32_e32 v27, v25
	v_mov_b32_e32 v26, v24
	s_nop 1
	v_permlane16_swap_b32 v25, v27
	v_permlane16_swap_b32 v24, v26
	s_waitcnt lgkmcnt(0)
	v_pk_add_f32 v[24:25], v[24:25], v[26:27]
	v_mov_b32_e32 v27, v25
	v_mov_b32_e32 v26, v24
	s_nop 1
	v_permlane32_swap_b32 v25, v27
	v_permlane32_swap_b32 v24, v26
	s_waitcnt lgkmcnt(0)
	v_pk_add_f32 v[24:25], v[24:25], v[26:27]
	s_nop 0
	v_pk_fma_f32 v[24:25], v[24:25], s[16:17], v[20:21] op_sel_hi:[1,0,0]
	s_nop 0
	v_mul_f32_e32 v26, 0x4b800000, v25
	v_cmp_gt_f32_e64 s[38:39], s71, v25
	v_cmp_gt_f32_e64 s[0:1], s71, v24
	s_nop 0
	v_cndmask_b32_e64 v25, v25, v26, s[38:39]
	v_rsq_f32_e32 v25, v25
	s_nop 0
	v_mul_f32_e32 v26, 0x45800000, v25
	v_cndmask_b32_e64 v25, v25, v26, s[38:39]
	v_mul_f32_e32 v26, v35, v25
	v_mul_f32_e32 v22, v26, v22
	v_mul_f32_e32 v26, v32, v25
	v_mul_f32_e32 v25, v33, v25
	v_mul_f32_e32 v25, v25, v14
	v_mul_f32_e32 v23, v26, v23
	v_mov_b32_e32 v26, v25
	v_mov_b32_e32 v102, v25
	s_nop 1
	v_permlane32_swap_b32 v26, v102
	v_cndmask_b32_e32 v26, v26, v102, vcc
	v_cvt_pk_bf16_f32 v22, v22, s0
	global_store_short v[18:19], v22, off offset:1920
	v_cvt_pk_bf16_f32 v22, v23, s0
	global_store_short v[18:19], v22, off offset:2048
	s_waitcnt lgkmcnt(0)
	v_mul_f32_e32 v26, v43, v26
	v_cndmask_b32_e64 v26, v26, -v26, vcc
	v_fmac_f32_e32 v26, v1, v25
	v_cvt_pk_bf16_f32 v22, v26, s0
	global_store_short v[18:19], v22, off offset:2176
	v_mul_f32_e32 v22, 0x4b800000, v24
	v_cndmask_b32_e64 v22, v24, v22, s[0:1]
	v_rsq_f32_e32 v22, v22
	s_nop 0
	v_mul_f32_e32 v23, 0x45800000, v22
	v_cndmask_b32_e64 v22, v22, v23, s[0:1]
	v_mul_f32_e32 v23, v30, v22
	v_mul_f32_e32 v24, v31, v22
	v_mul_f32_e32 v22, v34, v22
	v_mul_f32_e32 v22, v22, v29
	v_mul_f32_e32 v15, v24, v15
	v_mov_b32_e32 v24, v22
	v_mov_b32_e32 v102, v22
	s_nop 1
	v_permlane32_swap_b32 v24, v102
	v_cndmask_b32_e32 v24, v24, v102, vcc
	v_mul_f32_e32 v15, 0x3dd53b94, v15
	v_mul_f32_e32 v23, v23, v28
	v_cvt_pk_bf16_f32 v15, v15, s0
	global_store_short v[10:11], v15, off offset:2432
	s_waitcnt lgkmcnt(0)
; __device__ __forceinline__ float bf2f(unsigned short h) { return __uint_as_float(((unsigned)h) << 16); }
; __device__ __forceinline__ unsigned short f2bf(float f) { return (unsigned short)(cvt_pk_bf16(f, 0.f) & 0xffffu); }
; __device__ __forceinline__ void pass_qk_prep(const Params& P) {
;     ...
;         for (int h = 0; h < 8; ++h) {
;             bf16_t* q = QB + (size_t)t * 1536 + h * 192;
;             float a0 = bf2f(q[lane]), a1 = bf2f(q[64 + lane]), a2 = bf2f(q[128 + lane]);
;             float rs = rsqrtf(wave_sum(a0 * a0 + a1 * a1 + a2 * a2) * (1.f / 192.f) + EPS);
;             a0 *= rs * qn0; a1 *= rs * qn1; a2 *= rs * qn2;
;             float ot = __shfl_xor(a2, 32);
;             float r2 = lane < 32 ? a2 * cs - ot * sn : a2 * cs + ot * sn;
;             q[lane] = f2bf(a0 * QSC); q[64 + lane] = f2bf(a1 * QSC); q[128 + lane] = f2bf(r2 * QSC);
;             const bf16_t* kv = KVR + (size_t)t * 2048 + h * 256;
;             float b0 = bf2f(kv[lane]), b1 = bf2f(kv[64 + lane]), b2 = kpe;
;             rs = rsqrtf(wave_sum(b0 * b0 + b1 * b1 + b2 * b2) * (1.f / 192.f) + EPS);
;             b0 *= rs * kn0; b1 *= rs * kn1; b2 *= rs * kn2;
;             ot = __shfl_xor(b2, 32);
;             r2 = lane < 32 ? b2 * cs - ot * sn : b2 * cs + ot * sn;
;             bf16_t* k = KB + (size_t)t * 1536 + h * 192;
;             k[lane] = f2bf(b0); k[64 + lane] = f2bf(b1); k[128 + lane] = f2bf(r2);
	v_mul_f32_e32 v24, v43, v24
	v_cndmask_b32_e64 v24, v24, -v24, vcc
	v_fmac_f32_e32 v24, v1, v22
	v_mul_f32_e32 v22, 0x3dd53b94, v23
	v_mul_f32_e32 v15, 0x3dd53b94, v24
	v_cvt_pk_bf16_f32 v22, v22, s0
	v_cvt_pk_bf16_f32 v15, v15, s0
	global_store_short v[10:11], v22, off offset:2304
	global_store_short v[10:11], v15, off offset:2560
	v_mov_b32_e32 v15, v90
	s_nop 0
	v_mov_b32_e32 v22, v91
	v_lshlrev_b32_e32 v23, 16, v22
	v_lshlrev_b32_e32 v22, 16, v15
	v_mov_b32_e32 v15, v92
	v_mov_b32_e32 v27, v93
	v_mov_b32_e32 v28, v94
	v_pk_mul_f32 v[24:25], v[22:23], v[22:23]
	v_lshlrev_b32_e32 v15, 16, v15
	v_lshlrev_b32_e32 v29, 16, v28
	v_lshlrev_b32_e32 v28, 16, v27
	v_pk_mul_f32 v[44:45], v[28:29], v[28:29]
	v_mul_f32_e32 v26, v15, v15
	v_mov_b32_e32 v46, v44
	v_mov_b32_e32 v47, v24
	v_mov_b32_e32 v27, v25
	v_pk_add_f32 v[24:25], v[46:47], v[26:27]
	v_pk_mov_b32 v[26:27], v[44:45], v[16:17] op_sel:[1,0]
	s_nop 0
	v_pk_add_f32 v[24:25], v[24:25], v[26:27]
	s_nop 1
	v_mov_b32_dpp v27, v25 quad_perm:[1,0,3,2] row_mask:0xf bank_mask:0xf
	v_mov_b32_dpp v26, v24 quad_perm:[1,0,3,2] row_mask:0xf bank_mask:0xf
	s_waitcnt lgkmcnt(0)
	v_pk_add_f32 v[24:25], v[24:25], v[26:27]
	s_nop 1
	v_mov_b32_dpp v27, v25 quad_perm:[2,3,0,1] row_mask:0xf bank_mask:0xf
	v_mov_b32_dpp v26, v24 quad_perm:[2,3,0,1] row_mask:0xf bank_mask:0xf
	s_waitcnt lgkmcnt(0)
	v_pk_add_f32 v[24:25], v[24:25], v[26:27]
	s_nop 1
	v_mov_b32_dpp v27, v25 row_half_mirror row_mask:0xf bank_mask:0xf
	v_mov_b32_dpp v26, v24 row_half_mirror row_mask:0xf bank_mask:0xf
	s_waitcnt lgkmcnt(0)
	v_pk_add_f32 v[24:25], v[24:25], v[26:27]
	s_nop 1
	v_mov_b32_dpp v27, v25 row_mirror row_mask:0xf bank_mask:0xf
	v_mov_b32_dpp v26, v24 row_mirror row_mask:0xf bank_mask:0xf
	s_waitcnt lgkmcnt(0)
	v_pk_add_f32 v[24:25], v[24:25], v[26:27]
	v_mov_b32_e32 v27, v25
	v_mov_b32_e32 v26, v24
	s_nop 1
	v_permlane16_swap_b32 v25, v27
	v_permlane16_swap_b32 v24, v26
	s_waitcnt lgkmcnt(0)
	v_pk_add_f32 v[24:25], v[24:25], v[26:27]
	v_mov_b32_e32 v27, v25
	v_mov_b32_e32 v26, v24
	s_nop 1
	v_permlane32_swap_b32 v25, v27
	v_permlane32_swap_b32 v24, v26
	s_waitcnt lgkmcnt(0)
	v_pk_add_f32 v[24:25], v[24:25], v[26:27]
	s_nop 0
	v_pk_fma_f32 v[20:21], v[24:25], s[16:17], v[20:21] op_sel_hi:[1,0,0]
	s_nop 0
	v_mul_f32_e32 v17, 0x4b800000, v21
	v_cmp_gt_f32_e64 s[38:39], s71, v21
	v_cmp_gt_f32_e64 s[0:1], s71, v20
	s_nop 0
	v_cndmask_b32_e64 v17, v21, v17, s[38:39]
	v_rsq_f32_e32 v17, v17
	s_nop 0
	v_mul_f32_e32 v21, 0x45800000, v17
	v_cndmask_b32_e64 v17, v17, v21, s[38:39]
	v_mul_f32_e32 v21, v35, v17
	v_mul_f32_e32 v21, v21, v22
	v_mul_f32_e32 v22, v32, v17
	v_mul_f32_e32 v17, v33, v17
	v_mul_f32_e32 v17, v17, v14
	v_mul_f32_e32 v22, v22, v23
	v_mov_b32_e32 v23, v17
	v_mov_b32_e32 v102, v17
	s_nop 1
	v_permlane32_swap_b32 v23, v102
	v_cndmask_b32_e32 v23, v23, v102, vcc
	s_waitcnt lgkmcnt(0)
	v_mul_f32_e32 v23, v43, v23
	v_cndmask_b32_e64 v23, v23, -v23, vcc
	v_fmac_f32_e32 v23, v1, v17
	v_cvt_pk_bf16_f32 v17, v21, s0
	global_store_short v[18:19], v17, off offset:2304
	v_cvt_pk_bf16_f32 v17, v22, s0
	global_store_short v[18:19], v17, off offset:2432
	v_cvt_pk_bf16_f32 v17, v23, s0
	global_store_short v[18:19], v17, off offset:2560
	v_mul_f32_e32 v17, 0x4b800000, v20
	v_cndmask_b32_e64 v17, v20, v17, s[0:1]
	v_rsq_f32_e32 v17, v17
	s_nop 0
	v_mul_f32_e32 v20, 0x45800000, v17
	v_cndmask_b32_e64 v17, v17, v20, s[0:1]
	v_mul_f32_e32 v20, v30, v17
	v_mul_f32_e32 v21, v31, v17
	v_mul_f32_e32 v17, v34, v17
	v_mul_f32_e32 v17, v17, v29
	v_mul_f32_e32 v15, v21, v15
	v_mov_b32_e32 v21, v17
	v_mov_b32_e32 v102, v17
	s_nop 1
	v_permlane32_swap_b32 v21, v102
	v_cndmask_b32_e32 v21, v21, v102, vcc
	v_mul_f32_e32 v15, 0x3dd53b94, v15
	v_mul_f32_e32 v20, v20, v28
	v_cvt_pk_bf16_f32 v15, v15, s0
	global_store_short v[10:11], v15, off offset:2816
	s_waitcnt lgkmcnt(0)
	v_mul_f32_e32 v21, v43, v21
	v_cndmask_b32_e64 v21, v21, -v21, vcc
	v_fmac_f32_e32 v21, v1, v17
	v_mul_f32_e32 v17, 0x3dd53b94, v20
	v_mul_f32_e32 v15, 0x3dd53b94, v21
	v_cvt_pk_bf16_f32 v17, v17, s0
	v_cvt_pk_bf16_f32 v15, v15, s0
	global_store_short v[10:11], v17, off offset:2688
	global_store_short v[10:11], v15, off offset:2944
	v_mov_b32_e32 v10, v95
	s_nop 0
	v_mov_b32_e32 v11, v96
	v_lshlrev_b32_e32 v10, 16, v10
	v_lshlrev_b32_e32 v11, 16, v11
	v_pk_mul_f32 v[12:13], v[10:11], v[10:11]
	s_nop 0
	v_add_f32_e32 v12, v12, v13
	v_add_f32_e32 v12, v16, v12
	s_nop 1
	v_mov_b32_dpp v13, v12 quad_perm:[1,0,3,2] row_mask:0xf bank_mask:0xf
	s_waitcnt lgkmcnt(0)
	v_add_f32_e32 v12, v12, v13
	s_nop 1
	v_mov_b32_dpp v13, v12 quad_perm:[2,3,0,1] row_mask:0xf bank_mask:0xf
	s_waitcnt lgkmcnt(0)
	v_add_f32_e32 v12, v12, v13
	s_nop 1
	v_mov_b32_dpp v13, v12 row_half_mirror row_mask:0xf bank_mask:0xf
	s_waitcnt lgkmcnt(0)
	v_add_f32_e32 v12, v12, v13
	s_nop 1
	v_mov_b32_dpp v13, v12 row_mirror row_mask:0xf bank_mask:0xf
	s_waitcnt lgkmcnt(0)
	v_add_f32_e32 v12, v12, v13
	v_mov_b32_e32 v13, v12
	s_nop 1
	v_permlane16_swap_b32 v12, v13
	s_waitcnt lgkmcnt(0)
	v_add_f32_e32 v12, v12, v13
	v_mov_b32_e32 v13, v12
	s_nop 1
	v_permlane32_swap_b32 v12, v13
	s_waitcnt lgkmcnt(0)
	v_add_f32_e32 v12, v12, v13
	v_fmamk_f32 v12, v12, 0x3baaaaab, v203
	v_cmp_gt_f32_e64 s[0:1], s71, v12
	v_mul_f32_e32 v13, 0x4b800000, v12
	s_nop 0
	v_cndmask_b32_e64 v12, v12, v13, s[0:1]
	v_rsq_f32_e32 v12, v12
	s_nop 0
	v_mul_f32_e32 v13, 0x45800000, v12
	v_cndmask_b32_e64 v12, v12, v13, s[0:1]
	v_mul_f32_e32 v13, v35, v12
	v_mul_f32_e32 v10, v13, v10
	v_mul_f32_e32 v13, v32, v12
	v_mul_f32_e32 v12, v33, v12
	v_mul_f32_e32 v12, v12, v14
	v_mul_f32_e32 v11, v13, v11
	v_mov_b32_e32 v13, v12
	v_mov_b32_e32 v102, v12
	s_nop 1
	v_permlane32_swap_b32 v13, v102
	v_cndmask_b32_e32 v13, v13, v102, vcc
	s_waitcnt lgkmcnt(0)
	v_mul_f32_e32 v13, v43, v13
	v_cndmask_b32_e64 v13, v13, -v13, vcc
	v_fmac_f32_e32 v13, v1, v12
	v_cvt_pk_bf16_f32 v1, v10, s0
	global_store_short v[18:19], v1, off offset:2688
	v_cvt_pk_bf16_f32 v1, v11, s0
	global_store_short v[18:19], v1, off offset:2816
	v_cvt_pk_bf16_f32 v1, v13, s0
	v_cmp_lt_i32_e64 s[0:1], s15, v0
	s_or_b64 s[20:21], s[0:1], s[20:21]
	global_store_short v[18:19], v1, off offset:2944
	s_andn2_b64 exec, exec, s[20:21]
	s_cbranch_execnz .LBB0_202
